# v9 + low-rank pre-pass done by half of the workgroups (2 tasks/wave) so the two halves' GEMM store bursts are offset in time
# speedup vs baseline: 1.0048x; 1.0048x over previous
.LBB0_173:
	s_cmp_lt_i32 s40, 2
	s_cselect_b64 s[8:9], -1, 0
	s_and_b64 s[12:13], s[8:9], s[6:7]
	s_andn2_b64 vcc, exec, s[12:13]
	s_cbranch_vccnz .LBB0_217
	s_lshr_b32 s100, s2, 3
	s_and_b32 s101, s100, 1
	s_lshr_b32 s100, s100, 1
	s_lshl_b32 s100, s100, 3
	s_and_b32 s32, s2, 7
	s_or_b32 s100, s100, s32
	s_cmp_eq_u32 s101, 0
	s_cselect_b32 s100, 0x100, s100
	s_mov_b64 s[6:7], s[0:1]
	s_load_dwordx4 s[8:11], s[6:7], 0x60
	v_lshl_add_u32 v73, s100, 3, v140
	s_movk_i32 s3, 0x800
	v_lshlrev_b32_e32 v0, 4, v73
	v_cmp_gt_i32_e32 vcc, s3, v73
	v_and_b32_e32 v139, 15, v158
	v_mov_b32_e32 v69, 0
	v_cndmask_b32_e32 v0, 0, v0, vcc
	v_or_b32_e32 v0, v0, v139
	v_lshlrev_b32_e32 v56, 3, v158
	v_lshlrev_b32_e32 v74, 4, v158
	v_ashrrev_i32_e32 v1, 31, v0
	v_and_b32_e32 v70, 0x7f0, v74
	v_mov_b32_e32 v71, v69
	v_add_u32_e32 v52, 0x1000, v56
	v_bfe_u32 v64, v158, 4, 2
	v_lshlrev_b64 v[0:1], 11, v[0:1]
	s_waitcnt lgkmcnt(0)
	v_lshl_add_u64 v[48:49], s[10:11], 0, v[70:71]
	s_mov_b64 s[6:7], 0x1b00000
	v_and_b32_e32 v52, 0x3c00, v52
	v_lshl_add_u64 v[0:1], s[8:9], 0, v[0:1]
	v_lshlrev_b32_e32 v68, 4, v64
	v_lshl_add_u64 v[48:49], v[48:49], 0, s[6:7]
	v_and_b32_e32 v50, 0x3800, v74
	v_mov_b32_e32 v51, v69
	v_lshlrev_b32_e32 v52, 1, v52
	v_mov_b32_e32 v53, v69
	v_add_u32_e32 v54, 0x3000, v56
	v_lshl_add_u64 v[66:67], v[0:1], 0, v[68:69]
	v_lshl_add_u64 v[50:51], v[48:49], 0, v[50:51]
	v_lshl_add_u64 v[52:53], v[48:49], 0, v[52:53]
	s_movk_i32 s3, 0x4000
	v_and_b32_e32 v54, 0x7c00, v54
	global_load_dwordx4 v[0:3], v[66:67], off
	global_load_dwordx4 v[8:11], v[66:67], off offset:64
	global_load_dwordx4 v[4:7], v[66:67], off offset:128
	global_load_dwordx4 v[16:19], v[66:67], off offset:192
	global_load_dwordx4 v[12:15], v[66:67], off offset:256
	global_load_dwordx4 v[24:27], v[66:67], off offset:320
	global_load_dwordx4 v[20:23], v[66:67], off offset:384
	global_load_dwordx4 v[32:35], v[66:67], off offset:448
	global_load_dwordx4 v[28:31], v[66:67], off offset:512
	global_load_dwordx4 v[40:43], v[66:67], off offset:576
	global_load_dwordx4 v[36:39], v[66:67], off offset:640
	global_load_dwordx4 v[44:47], v[66:67], off offset:704
	global_load_dwordx4 v[76:79], v[50:51], off
	global_load_dwordx4 v[80:83], v[52:53], off
	v_add_co_u32_e64 v52, s[6:7], s3, v50
	v_lshlrev_b32_e32 v54, 1, v54
	v_mov_b32_e32 v55, v69
	v_addc_co_u32_e64 v53, s[6:7], 0, v51, s[6:7]
	v_lshl_add_u64 v[54:55], v[48:49], 0, v[54:55]
	global_load_dwordx4 v[84:87], v[52:53], off
	global_load_dwordx4 v[88:91], v[54:55], off
	s_mov_b32 s3, 0x8000
	v_add_u32_e32 v54, 0x5000, v56
	v_add_co_u32_e64 v52, s[6:7], s3, v50
	v_and_b32_e32 v54, 0x7c00, v54
	s_nop 0
	v_addc_co_u32_e64 v53, s[6:7], 0, v51, s[6:7]
	v_lshlrev_b32_e32 v54, 1, v54
	v_mov_b32_e32 v55, v69
	v_lshl_add_u64 v[54:55], v[48:49], 0, v[54:55]
	global_load_dwordx4 v[92:95], v[52:53], off
	global_load_dwordx4 v[96:99], v[54:55], off
	s_mov_b32 s3, 0xc000
	v_add_co_u32_e64 v50, s[6:7], s3, v50
	v_add_u32_e32 v65, 0, v70
	s_nop 0
	v_addc_co_u32_e64 v51, s[6:7], 0, v51, s[6:7]
	global_load_dwordx4 v[100:103], v[50:51], off
	v_add_u32_e32 v50, 0x7000, v56
	v_and_b32_e32 v50, 0xfc00, v50
	v_lshlrev_b32_e32 v50, 1, v50
	v_mov_b32_e32 v51, v69
	v_lshl_add_u64 v[108:109], v[48:49], 0, v[50:51]
	global_load_dwordx4 v[104:107], v[108:109], off
	global_load_dwordx4 v[52:55], v[66:67], off offset:768
	global_load_dwordx4 v[60:63], v[66:67], off offset:832
	global_load_dwordx4 v[56:59], v[66:67], off offset:896
	global_load_dwordx4 v[48:51], v[66:67], off offset:960
	v_add_u32_e32 v67, 0x200, v158
	v_lshrrev_b32_e32 v72, 7, v158
	s_movk_i32 s6, 0x810
	v_lshrrev_b32_e32 v67, 7, v67
	v_mad_u32_u24 v66, v72, s6, v65
	v_mad_u32_u24 v67, v67, s6, v65
	s_load_dword s3, s[0:1], 0x78
	s_mov_b32 s16, 0
	s_waitcnt vmcnt(11)
	ds_write_b128 v66, v[76:79]
	s_waitcnt vmcnt(10)
	ds_write_b128 v67, v[80:83]
	s_waitcnt vmcnt(9)
	ds_write_b128 v66, v[84:87] offset:16512
	v_add_u32_e32 v67, 0x600, v158
	v_lshrrev_b32_e32 v67, 7, v67
	v_mad_u32_u24 v67, v67, s6, v65
	s_waitcnt vmcnt(8)
	ds_write_b128 v67, v[88:91]
	s_waitcnt vmcnt(7)
	ds_write_b128 v66, v[92:95] offset:33024
	v_add_u32_e32 v67, 0xa00, v158
	v_lshrrev_b32_e32 v67, 7, v67
	v_mad_u32_u24 v67, v67, s6, v65
	s_waitcnt vmcnt(6)
	ds_write_b128 v67, v[96:99]
	s_waitcnt vmcnt(5)
	ds_write_b128 v66, v[100:103] offset:49536
	v_add_u32_e32 v66, 0xe00, v158
	v_lshrrev_b32_e32 v66, 7, v66
	v_mad_u32_u24 v65, v66, s6, v65
	s_waitcnt vmcnt(4)
	ds_write_b128 v65, v[104:107]
	s_waitcnt lgkmcnt(0)
	s_barrier
	s_and_saveexec_b64 s[6:7], vcc
	s_cbranch_execz .LBB0_179
	v_mul_u32_u24_e32 v70, 0x810, v139
	v_lshlrev_b32_e32 v64, 3, v64
	v_lshl_add_u64 v[66:67], s[10:11], 0, v[68:69]
	v_add3_u32 v75, 0, v70, v68
	v_lshlrev_b32_e32 v68, 4, v140
	v_lshlrev_b32_e32 v64, 1, v64
	v_mov_b32_e32 v65, v69
	s_mov_b64 s[14:15], 0x500000
	v_lshl_add_u32 v68, s100, 7, v68
	s_movk_i32 s17, 0x400
	v_lshl_add_u64 v[64:65], s[8:9], 0, v[64:65]
	v_lshl_add_u64 v[66:67], v[66:67], 0, s[14:15]
	v_or_b32_e32 v68, v68, v139
	s_movk_i32 s18, 0x4000
	s_mov_b64 s[14:15], 0
	s_movk_i32 s19, 0x7ff
	s_branch .LBB0_177
